# grid barrier: all workgroups poll the cross-XCD generation; leaders no longer re-publish the release per XCD
# speedup vs baseline: 1.0005x; 1.0005x over previous
.LBB0_312:
	s_or_b64 exec, exec, s[4:5]
	s_mov_b64 s[4:5], exec
	v_mbcnt_lo_u32_b32 v0, s4, 0
	v_mbcnt_hi_u32_b32 v0, s5, v0
	v_cmp_eq_u32_e32 vcc, 0, v0
	s_waitcnt vmcnt(0)
	buffer_inv sc1
	s_and_saveexec_b64 s[6:7], vcc
	s_cbranch_execz .LBB0_314
	s_bcnt1_i32_b64 s0, s[4:5]
	v_mov_b32_e32 v0, s0
	v_readlane_b32 s0, v255, 9
	v_readlane_b32 s1, v255, 10
	s_nop 4
	s_nop 0

.LBB0_1699:
	s_bcnt1_i32_b64 s0, s[4:5]
	v_mov_b32_e32 v0, s0
	v_readlane_b32 s0, v255, 9
	v_readlane_b32 s1, v255, 10
	s_nop 4
	s_nop 0
	s_getpc_b64 s[98:99]
